# v31 = v30 + steady-loop per-step barrier waits vmcnt(3) only
# baseline (speedup 1.0000x reference)
.Lstg_mid1:
	ds_read_b64_tr_b16 v[40:41], v167 offset:54272
	ds_read_b64_tr_b16 v[42:43], v167 offset:54784
	s_waitcnt lgkmcnt(6)
	v_mfma_f32_32x32x16_bf16 v[16:31], v[132:135], v[32:35], v[16:31]
	ds_read_b64_tr_b16 v[32:33], v167 offset:51200
	ds_read_b64_tr_b16 v[34:35], v167 offset:51712
	s_waitcnt lgkmcnt(6)
	v_mfma_f32_32x32x16_bf16 v[0:15], v[132:135], v[48:51], v[0:15]
	ds_read_b64_tr_b16 v[44:45], v167 offset:55296
	ds_read_b64_tr_b16 v[46:47], v167 offset:55808
	s_waitcnt lgkmcnt(6)
	v_mfma_f32_32x32x16_bf16 v[16:31], v[128:131], v[36:39], v[16:31]
	v_exp_f32_e32 v80, v80
	v_exp_f32_e32 v81, v81
	v_exp_f32_e32 v82, v82
	v_exp_f32_e32 v83, v83
	ds_read_b64_tr_b16 v[48:49], v167 offset:52224
	ds_read_b64_tr_b16 v[50:51], v167 offset:52736
	s_waitcnt lgkmcnt(6)
	v_mfma_f32_32x32x16_bf16 v[0:15], v[128:131], v[40:43], v[0:15]
	v_exp_f32_e32 v84, v84
	v_exp_f32_e32 v85, v85
	v_exp_f32_e32 v86, v86
	v_exp_f32_e32 v87, v87
	ds_read_b64_tr_b16 v[40:41], v167 offset:56320
	ds_read_b64_tr_b16 v[42:43], v167 offset:56832
	s_waitcnt lgkmcnt(6)
	v_mfma_f32_32x32x16_bf16 v[16:31], v[124:127], v[32:35], v[16:31]
	v_exp_f32_e32 v88, v88
	v_exp_f32_e32 v89, v89
	v_exp_f32_e32 v90, v90
	v_exp_f32_e32 v91, v91
	v_add_u32_e32 v142, s83, v179
	ds_read_b128 v[32:35], v142
	s_waitcnt lgkmcnt(5)
	v_mfma_f32_32x32x16_bf16 v[0:15], v[124:127], v[44:47], v[0:15]
	v_exp_f32_e32 v92, v92
	v_exp_f32_e32 v93, v93
	v_exp_f32_e32 v94, v94
	v_exp_f32_e32 v95, v95
	ds_read_b128 v[36:39], v142 offset:512
	s_waitcnt lgkmcnt(4)
	v_mfma_f32_32x32x16_bf16 v[16:31], v[120:123], v[48:51], v[16:31]
	v_exp_f32_e32 v64, v64
	v_exp_f32_e32 v65, v65
	v_exp_f32_e32 v66, v66
	v_exp_f32_e32 v67, v67
	ds_read_b128 v[136:139], v142 offset:2048
	s_waitcnt lgkmcnt(3)
	v_mfma_f32_32x32x16_bf16 v[0:15], v[120:123], v[40:43], v[0:15]
	v_exp_f32_e32 v68, v68
	v_exp_f32_e32 v69, v69
	v_exp_f32_e32 v70, v70
	v_exp_f32_e32 v71, v71
	v_exp_f32_e32 v72, v72
	v_exp_f32_e32 v73, v73
	v_exp_f32_e32 v74, v74
	v_exp_f32_e32 v75, v75
	v_exp_f32_e32 v76, v76
	v_exp_f32_e32 v77, v77
	v_exp_f32_e32 v78, v78
	v_exp_f32_e32 v79, v79
	s_cmp_lt_u32 s90, 4
	s_cbranch_scc0 .Lstg_end1
	s_waitcnt vmcnt(3)
	s_barrier

.Lstg_mid2:
	s_add_i32 s0, s83, 0x3000
	s_cmpk_lg_u32 s83, 0x9000
	s_cselect_b32 s82, s0, 0
	ds_read_b64_tr_b16 v[72:73], v141 offset:54272
	ds_read_b64_tr_b16 v[74:75], v141 offset:54784
	s_waitcnt lgkmcnt(6)
	v_mfma_f32_32x32x16_bf16 v[16:31], v[132:135], v[64:67], v[16:31]
	ds_read_b64_tr_b16 v[64:65], v141 offset:51200
	ds_read_b64_tr_b16 v[66:67], v141 offset:51712
	s_waitcnt lgkmcnt(6)
	v_mfma_f32_32x32x16_bf16 v[0:15], v[132:135], v[80:83], v[0:15]
	s_add_i32 s0, s79, 0x2000
	s_cmpk_lg_i32 s79, 0x4000
	s_cselect_b32 s0, s0, 0xe800
	s_cmpk_lg_u32 s79, 0xe800
	s_cselect_b32 s84, s0, 0
	ds_read_b64_tr_b16 v[76:77], v141 offset:55296
	ds_read_b64_tr_b16 v[78:79], v141 offset:55808
	s_waitcnt lgkmcnt(6)
	v_mfma_f32_32x32x16_bf16 v[16:31], v[128:131], v[68:71], v[16:31]
	v_exp_f32_e32 v48, v48
	v_exp_f32_e32 v49, v49
	v_exp_f32_e32 v50, v50
	v_exp_f32_e32 v51, v51
	s_add_i32 s0, s82, 0x3000
	s_cmpk_lg_u32 s82, 0x9000
	s_cselect_b32 s85, s0, 0
	ds_read_b64_tr_b16 v[68:69], v141 offset:52224
	ds_read_b64_tr_b16 v[70:71], v141 offset:52736
	s_waitcnt lgkmcnt(6)
	v_mfma_f32_32x32x16_bf16 v[0:15], v[128:131], v[72:75], v[0:15]
	v_exp_f32_e32 v52, v52
	v_exp_f32_e32 v53, v53
	v_exp_f32_e32 v54, v54
	v_exp_f32_e32 v55, v55
	s_add_u32 s68, s68, 0x30000
	s_addc_u32 s69, s69, 0
	ds_read_b64_tr_b16 v[72:73], v141 offset:56320
	ds_read_b64_tr_b16 v[74:75], v141 offset:56832
	s_waitcnt lgkmcnt(6)
	v_mfma_f32_32x32x16_bf16 v[16:31], v[124:127], v[64:67], v[16:31]
	v_exp_f32_e32 v56, v56
	v_exp_f32_e32 v57, v57
	v_exp_f32_e32 v58, v58
	v_exp_f32_e32 v59, v59
	s_add_u32 s48, s48, 0x48000
	s_addc_u32 s49, s49, 0
	v_add_u32_e32 v64, s82, v179
	ds_read_b128 v[80:83], v64
	s_waitcnt lgkmcnt(5)
	v_mfma_f32_32x32x16_bf16 v[0:15], v[124:127], v[76:79], v[0:15]
	v_exp_f32_e32 v60, v60
	v_exp_f32_e32 v61, v61
	v_exp_f32_e32 v62, v62
	v_exp_f32_e32 v63, v63
	s_add_u32 s8, s8, 0x2000
	s_addc_u32 s9, s9, 0
	ds_read_b128 v[136:139], v64 offset:512
	s_waitcnt lgkmcnt(4)
	v_mfma_f32_32x32x16_bf16 v[16:31], v[120:123], v[68:71], v[16:31]
	v_exp_f32_e32 v32, v32
	v_exp_f32_e32 v33, v33
	v_exp_f32_e32 v34, v34
	v_exp_f32_e32 v35, v35
	s_add_i32 s0, s87, 2
	ds_read_b128 v[140:143], v64 offset:2048
	s_waitcnt lgkmcnt(3)
	v_mfma_f32_32x32x16_bf16 v[0:15], v[120:123], v[72:75], v[0:15]
	v_exp_f32_e32 v36, v36
	v_exp_f32_e32 v37, v37
	v_exp_f32_e32 v38, v38
	v_exp_f32_e32 v39, v39
	v_exp_f32_e32 v40, v40
	v_exp_f32_e32 v41, v41
	v_exp_f32_e32 v42, v42
	v_exp_f32_e32 v43, v43
	v_exp_f32_e32 v44, v44
	v_exp_f32_e32 v45, v45
	v_exp_f32_e32 v46, v46
	v_exp_f32_e32 v47, v47
	s_cmp_lt_u32 s90, 4
	s_cbranch_scc0 .Lstg_end2
	s_waitcnt vmcnt(3)
	s_barrier
